# gMLP output stores widened from 32 x 8-byte to 16 x 16-byte per lane (v_permlane32_swap pairs lanes l and l+32); the per-CU store path is paid per lane address, not per byte
# speedup vs baseline: 1.0096x; 1.0073x over previous
; #define LAS __attribute__((address_space(3)))
; __device__ __forceinline__ unsigned pk2(float lo, float hi) { f32x2 v = {lo, hi}; bf16x2_t b = __builtin_convertvector(v, bf16x2_t); return __builtin_bit_cast(unsigned, b); }
; __device__ __forceinline__ void gmlp_unit(const GmlpP& P, int b, int ch, LAS unsigned char* lds, int wave, int lane_in) {
;     ...
; #pragma unroll
;     for (int nt = 0; nt < 2; ++nt) {
;         const int t = 32 * (nt == 0 ? tt0 : tt1) + r32;
;         const float tot = (ssqg[t] + ssqg[128 + t]) + (ssqg[256 + t] + ssqg[384 + t]);
;         const float r = __builtin_amdgcn_rsqf(tot * (1.0f / GW) + EPS);
;         bf16_t* op = P.MIX + (tok0 + t) * DM + AW + gI * 128 + 4 * h;
; #pragma unroll
;         for (int mt = 0; mt < 4; ++mt)
; #pragma unroll
;             for (int e4 = 0; e4 < 4; ++e4) {
;                 const f32x4 gg = *(const LAS f32x4*)(lds + LDS_GG + (gI * 128 + 32 * mt + 8 * e4 + 4 * h) * 4);
;                 u32x2 w; w.x = pk2(acc[mt][nt][4 * e4] * r * gg[0], acc[mt][nt][4 * e4 + 1] * r * gg[1]); w.y = pk2(acc[mt][nt][4 * e4 + 2] * r * gg[2], acc[mt][nt][4 * e4 + 3] * r * gg[3]);
;                 *(u32x2*)(op + 32 * mt + 8 * e4) = w;
;             }
;     }
.LBB0_536:
	s_or_b64 exec, exec, s[26:27]
	s_add_i32 s18, 0, 0x22000
	v_lshl_add_u32 v4, v157, 2, s18
	s_waitcnt lgkmcnt(0)
	s_barrier
	ds_read2st64_b32 v[2:3], v4 offset1:2
	ds_read2st64_b32 v[4:5], v4 offset0:4 offset1:6
	v_add_u32_e32 v6, s28, v144
	s_add_i32 s26, 0, 0x22800
	v_lshl_add_u32 v153, v6, 2, s26
	s_waitcnt lgkmcnt(1)
	v_mov_b32_e32 v6, v2
	s_waitcnt lgkmcnt(0)
	v_mov_b32_e32 v7, v4
	v_mov_b32_e32 v4, v3
	v_pk_add_f32 v[2:3], v[6:7], v[4:5]
	v_lshlrev_b32_e32 v140, 11, v156
	v_add_f32_e32 v2, v2, v3
	v_fmamk_f32 v2, v2, 0x3b000000, v1
	v_add_u32_e32 v4, s6, v144
	v_rsq_f32_e32 v152, v2
	v_lshl_add_u64 v[2:3], s[16:17], 0, v[140:141]
	v_lshl_add_u32 v140, v4, 2, s26
	ds_read_b128 v[6:9], v140
	v_lshlrev_b64 v[150:151], 1, v[144:145]
	v_lshl_add_u64 v[154:155], v[2:3], 0, v[150:151]
	ds_read_b128 v[2:5], v140 offset:32
	v_pk_mul_f32 v[10:11], v[114:115], v[152:153] op_sel_hi:[1,0]
	v_pk_mul_f32 v[12:13], v[116:117], v[152:153] op_sel_hi:[1,0]
	s_waitcnt lgkmcnt(1)
	v_pk_mul_f32 v[10:11], v[6:7], v[10:11]
	v_pk_mul_f32 v[12:13], v[8:9], v[12:13]
	v_cvt_pk_bf16_f32 v10, v10, v11
	v_cvt_pk_bf16_f32 v11, v12, v13
	v_and_b32_e32 v222, 32, v0
	v_lshrrev_b32_e32 v222, 2, v222
	v_mov_b32_e32 v223, 0
	v_lshl_add_u64 v[218:219], v[154:155], 0, v[222:223]
	v_mov_b32_e32 v202, v10
	v_mov_b32_e32 v203, v11
	v_pk_mul_f32 v[10:11], v[118:119], v[152:153] op_sel_hi:[1,0]
	v_pk_mul_f32 v[118:119], v[122:123], v[152:153] op_sel_hi:[1,0]
	s_waitcnt lgkmcnt(0)
	v_pk_mul_f32 v[10:11], v[2:3], v[10:11]
	v_pk_mul_f32 v[120:121], v[120:121], v[152:153] op_sel_hi:[1,0]
	v_cvt_pk_bf16_f32 v114, v10, v11
	v_pk_mul_f32 v[10:11], v[130:131], v[152:153] op_sel_hi:[1,0]
	v_pk_mul_f32 v[98:99], v[98:99], v[152:153] op_sel_hi:[1,0]
	v_pk_mul_f32 v[116:117], v[4:5], v[10:11]
	ds_read_b128 v[10:13], v140 offset:64
	v_cvt_pk_bf16_f32 v115, v116, v117
	v_mov_b32_e32 v204, v114
	v_mov_b32_e32 v205, v115
	s_nop 1
	v_permlane32_swap_b32_e32 v202, v204
	v_permlane32_swap_b32_e32 v203, v205
	global_store_dwordx4 v[218:219], v[202:205], off offset:1024
	ds_read_b128 v[114:117], v140 offset:96
	v_pk_mul_f32 v[100:101], v[100:101], v[152:153] op_sel_hi:[1,0]
	s_waitcnt lgkmcnt(1)
	v_pk_mul_f32 v[118:119], v[10:11], v[118:119]
	v_pk_mul_f32 v[120:121], v[12:13], v[120:121]
	v_cvt_pk_bf16_f32 v118, v118, v119
	v_cvt_pk_bf16_f32 v119, v120, v121
	v_mov_b32_e32 v206, v118
	v_mov_b32_e32 v207, v119
	v_pk_mul_f32 v[118:119], v[124:125], v[152:153] op_sel_hi:[1,0]
	v_pk_mul_f32 v[104:105], v[104:105], v[152:153] op_sel_hi:[1,0]
	s_waitcnt lgkmcnt(0)
	v_pk_mul_f32 v[118:119], v[118:119], v[114:115]
	v_pk_mul_f32 v[82:83], v[82:83], v[152:153] op_sel_hi:[1,0]
	v_cvt_pk_bf16_f32 v122, v118, v119
	v_pk_mul_f32 v[118:119], v[126:127], v[152:153] op_sel_hi:[1,0]
	v_pk_mul_f32 v[84:85], v[84:85], v[152:153] op_sel_hi:[1,0]
	v_pk_mul_f32 v[124:125], v[118:119], v[116:117]
	v_add_u32_e32 v118, s29, v144
	v_lshl_add_u32 v130, v118, 2, s26
	ds_read_b128 v[118:121], v130
	v_cvt_pk_bf16_f32 v123, v124, v125
	v_mov_b32_e32 v208, v122
	v_mov_b32_e32 v209, v123
	s_nop 1
	v_permlane32_swap_b32_e32 v206, v208
	v_permlane32_swap_b32_e32 v207, v209
	global_store_dwordx4 v[218:219], v[206:209], off offset:1056
	ds_read_b128 v[122:125], v130 offset:32
	v_pk_mul_f32 v[88:89], v[88:89], v[152:153] op_sel_hi:[1,0]
	s_waitcnt lgkmcnt(1)
	v_pk_mul_f32 v[98:99], v[98:99], v[118:119]
	v_pk_mul_f32 v[100:101], v[100:101], v[120:121]
	v_cvt_pk_bf16_f32 v98, v98, v99
	v_cvt_pk_bf16_f32 v99, v100, v101
	v_mov_b32_e32 v210, v98
	v_mov_b32_e32 v211, v99
	v_pk_mul_f32 v[98:99], v[102:103], v[152:153] op_sel_hi:[1,0]
	v_pk_mul_f32 v[66:67], v[66:67], v[152:153] op_sel_hi:[1,0]
	s_waitcnt lgkmcnt(0)
	v_pk_mul_f32 v[98:99], v[98:99], v[122:123]
	v_pk_mul_f32 v[68:69], v[68:69], v[152:153] op_sel_hi:[1,0]
	v_cvt_pk_bf16_f32 v102, v98, v99
	v_pk_mul_f32 v[98:99], v[128:129], v[152:153] op_sel_hi:[1,0]
	v_pk_mul_f32 v[72:73], v[72:73], v[152:153] op_sel_hi:[1,0]
	v_pk_mul_f32 v[126:127], v[98:99], v[124:125]
	ds_read_b128 v[98:101], v130 offset:64
	v_cvt_pk_bf16_f32 v103, v126, v127
	ds_read_b128 v[126:129], v130 offset:96
	v_mov_b32_e32 v212, v102
	v_mov_b32_e32 v213, v103
	s_nop 1
	v_permlane32_swap_b32_e32 v210, v212
	v_permlane32_swap_b32_e32 v211, v213
	global_store_dwordx4 v[218:219], v[210:213], off offset:1088
	v_pk_mul_f32 v[102:103], v[106:107], v[152:153] op_sel_hi:[1,0]
	s_waitcnt lgkmcnt(1)
	v_pk_mul_f32 v[104:105], v[104:105], v[100:101]
	v_pk_mul_f32 v[102:103], v[102:103], v[98:99]
	v_lshlrev_b32_e32 v140, 11, v139
	v_cvt_pk_bf16_f32 v102, v102, v103
	v_cvt_pk_bf16_f32 v103, v104, v105
	v_mov_b32_e32 v214, v102
	v_mov_b32_e32 v215, v103
	v_pk_mul_f32 v[102:103], v[108:109], v[152:153] op_sel_hi:[1,0]
	s_add_i32 s49, s49, s100
	s_waitcnt lgkmcnt(0)
	v_pk_mul_f32 v[102:103], v[102:103], v[126:127]
	s_add_i32 s38, s38, s39
	v_cvt_pk_bf16_f32 v106, v102, v103
	v_pk_mul_f32 v[102:103], v[110:111], v[152:153] op_sel_hi:[1,0]
	s_cmp_gt_i32 s49, s101
	v_pk_mul_f32 v[108:109], v[102:103], v[128:129]
	v_add_u32_e32 v102, s30, v144
	v_lshl_add_u32 v130, v102, 2, s26
	ds_read_b128 v[102:105], v130
	v_cvt_pk_bf16_f32 v107, v108, v109
	v_mov_b32_e32 v216, v106
	v_mov_b32_e32 v217, v107
	s_nop 1
	v_permlane32_swap_b32_e32 v214, v216
	v_permlane32_swap_b32_e32 v215, v217
	global_store_dwordx4 v[218:219], v[214:217], off offset:1120
	ds_read_b128 v[106:109], v130 offset:32
	s_waitcnt lgkmcnt(1)
	v_pk_mul_f32 v[82:83], v[82:83], v[102:103]
	v_pk_mul_f32 v[84:85], v[84:85], v[104:105]
	v_cvt_pk_bf16_f32 v82, v82, v83
	v_cvt_pk_bf16_f32 v83, v84, v85
	v_mov_b32_e32 v202, v82
	v_mov_b32_e32 v203, v83
	v_pk_mul_f32 v[82:83], v[86:87], v[152:153] op_sel_hi:[1,0]
	s_waitcnt lgkmcnt(0)
; #define LAS __attribute__((address_space(3)))
; __device__ __forceinline__ unsigned pk2(float lo, float hi) { f32x2 v = {lo, hi}; bf16x2_t b = __builtin_convertvector(v, bf16x2_t); return __builtin_bit_cast(unsigned, b); }
; __device__ __forceinline__ void gmlp_unit(const GmlpP& P, int b, int ch, LAS unsigned char* lds, int wave, int lane_in) {
;     ...
; #pragma unroll
;     for (int nt = 0; nt < 2; ++nt) {
;         const int t = 32 * (nt == 0 ? tt0 : tt1) + r32;
;         const float tot = (ssqg[t] + ssqg[128 + t]) + (ssqg[256 + t] + ssqg[384 + t]);
;         const float r = __builtin_amdgcn_rsqf(tot * (1.0f / GW) + EPS);
;         bf16_t* op = P.MIX + (tok0 + t) * DM + AW + gI * 128 + 4 * h;
; #pragma unroll
;         for (int mt = 0; mt < 4; ++mt)
; #pragma unroll
;             for (int e4 = 0; e4 < 4; ++e4) {
;                 const f32x4 gg = *(const LAS f32x4*)(lds + LDS_GG + (gI * 128 + 32 * mt + 8 * e4 + 4 * h) * 4);
;                 u32x2 w; w.x = pk2(acc[mt][nt][4 * e4] * r * gg[0], acc[mt][nt][4 * e4 + 1] * r * gg[1]); w.y = pk2(acc[mt][nt][4 * e4 + 2] * r * gg[2], acc[mt][nt][4 * e4 + 3] * r * gg[3]);
;                 *(u32x2*)(op + 32 * mt + 8 * e4) = w;
;             }
;     }
	v_pk_mul_f32 v[82:83], v[82:83], v[106:107]
	s_nop 0
	v_cvt_pk_bf16_f32 v86, v82, v83
	v_pk_mul_f32 v[82:83], v[112:113], v[152:153] op_sel_hi:[1,0]
	s_nop 0
	v_pk_mul_f32 v[110:111], v[82:83], v[108:109]
	ds_read_b128 v[82:85], v130 offset:64
	v_cvt_pk_bf16_f32 v87, v110, v111
	ds_read_b128 v[110:113], v130 offset:96
	v_mov_b32_e32 v204, v86
	v_mov_b32_e32 v205, v87
	s_nop 1
	v_permlane32_swap_b32_e32 v202, v204
	v_permlane32_swap_b32_e32 v203, v205
	global_store_dwordx4 v[218:219], v[202:205], off offset:1152
	v_pk_mul_f32 v[86:87], v[90:91], v[152:153] op_sel_hi:[1,0]
	s_waitcnt lgkmcnt(1)
	v_pk_mul_f32 v[88:89], v[88:89], v[84:85]
	v_pk_mul_f32 v[86:87], v[86:87], v[82:83]
	s_nop 0
	v_cvt_pk_bf16_f32 v86, v86, v87
	v_cvt_pk_bf16_f32 v87, v88, v89
	v_mov_b32_e32 v206, v86
	v_mov_b32_e32 v207, v87
	v_pk_mul_f32 v[86:87], v[92:93], v[152:153] op_sel_hi:[1,0]
	s_waitcnt lgkmcnt(0)
	v_pk_mul_f32 v[86:87], v[86:87], v[110:111]
	s_nop 0
	v_cvt_pk_bf16_f32 v90, v86, v87
	v_pk_mul_f32 v[86:87], v[94:95], v[152:153] op_sel_hi:[1,0]
	s_nop 0
	v_pk_mul_f32 v[92:93], v[86:87], v[112:113]
	ds_read_b128 v[86:89], v153
	v_cvt_pk_bf16_f32 v91, v92, v93
	v_mov_b32_e32 v208, v90
	v_mov_b32_e32 v209, v91
	s_nop 1
	v_permlane32_swap_b32_e32 v206, v208
	v_permlane32_swap_b32_e32 v207, v209
	global_store_dwordx4 v[218:219], v[206:209], off offset:1184
	ds_read_b128 v[90:93], v153 offset:32
	s_waitcnt lgkmcnt(1)
	v_pk_mul_f32 v[66:67], v[66:67], v[86:87]
	v_pk_mul_f32 v[68:69], v[68:69], v[88:89]
	v_cvt_pk_bf16_f32 v66, v66, v67
	v_cvt_pk_bf16_f32 v67, v68, v69
	v_mov_b32_e32 v210, v66
	v_mov_b32_e32 v211, v67
	v_pk_mul_f32 v[66:67], v[70:71], v[152:153] op_sel_hi:[1,0]
	s_waitcnt lgkmcnt(0)
	v_pk_mul_f32 v[66:67], v[66:67], v[90:91]
	s_nop 0
	v_cvt_pk_bf16_f32 v70, v66, v67
	v_pk_mul_f32 v[66:67], v[96:97], v[152:153] op_sel_hi:[1,0]
	s_nop 0
	v_pk_mul_f32 v[94:95], v[66:67], v[92:93]
	ds_read_b128 v[66:69], v153 offset:64
	v_cvt_pk_bf16_f32 v71, v94, v95
	ds_read_b128 v[94:97], v153 offset:96
	v_mov_b32_e32 v212, v70
	v_mov_b32_e32 v213, v71
	s_nop 1
	v_permlane32_swap_b32_e32 v210, v212
	v_permlane32_swap_b32_e32 v211, v213
	global_store_dwordx4 v[218:219], v[210:213], off offset:1216
	v_pk_mul_f32 v[70:71], v[74:75], v[152:153] op_sel_hi:[1,0]
	s_waitcnt lgkmcnt(1)
	v_pk_mul_f32 v[72:73], v[72:73], v[68:69]
	v_pk_mul_f32 v[70:71], v[70:71], v[66:67]
	s_nop 0
	v_cvt_pk_bf16_f32 v70, v70, v71
	v_cvt_pk_bf16_f32 v71, v72, v73
	v_mov_b32_e32 v214, v70
	v_mov_b32_e32 v215, v71
	v_pk_mul_f32 v[70:71], v[76:77], v[152:153] op_sel_hi:[1,0]
	v_pk_mul_f32 v[72:73], v[78:79], v[152:153] op_sel_hi:[1,0]
	s_waitcnt lgkmcnt(0)
	v_pk_mul_f32 v[70:71], v[70:71], v[94:95]
	v_pk_mul_f32 v[72:73], v[72:73], v[96:97]
	v_cvt_pk_bf16_f32 v70, v70, v71
	v_lshl_add_u32 v71, v158, 2, s18
	ds_read2st64_b32 v[74:75], v71 offset1:2
	ds_read2st64_b32 v[76:77], v71 offset0:4 offset1:6
	v_cvt_pk_bf16_f32 v71, v72, v73
	v_mov_b32_e32 v216, v70
	v_mov_b32_e32 v217, v71
	s_nop 1
	v_permlane32_swap_b32_e32 v214, v216
	v_permlane32_swap_b32_e32 v215, v217
	global_store_dwordx4 v[218:219], v[214:217], off offset:1248
	v_lshl_add_u64 v[72:73], s[16:17], 0, v[140:141]
	s_waitcnt lgkmcnt(1)
	v_mov_b32_e32 v70, v74
	s_waitcnt lgkmcnt(0)
; #define LAS __attribute__((address_space(3)))
; __device__ __forceinline__ unsigned pk2(float lo, float hi) { f32x2 v = {lo, hi}; bf16x2_t b = __builtin_convertvector(v, bf16x2_t); return __builtin_bit_cast(unsigned, b); }
; __device__ __forceinline__ void gmlp_unit(const GmlpP& P, int b, int ch, LAS unsigned char* lds, int wave, int lane_in) {
;     ...
; #pragma unroll
;     for (int nt = 0; nt < 2; ++nt) {
;         const int t = 32 * (nt == 0 ? tt0 : tt1) + r32;
;         const float tot = (ssqg[t] + ssqg[128 + t]) + (ssqg[256 + t] + ssqg[384 + t]);
;         const float r = __builtin_amdgcn_rsqf(tot * (1.0f / GW) + EPS);
;         bf16_t* op = P.MIX + (tok0 + t) * DM + AW + gI * 128 + 4 * h;
; #pragma unroll
;         for (int mt = 0; mt < 4; ++mt)
; #pragma unroll
;             for (int e4 = 0; e4 < 4; ++e4) {
;                 const f32x4 gg = *(const LAS f32x4*)(lds + LDS_GG + (gI * 128 + 32 * mt + 8 * e4 + 4 * h) * 4);
;                 u32x2 w; w.x = pk2(acc[mt][nt][4 * e4] * r * gg[0], acc[mt][nt][4 * e4 + 1] * r * gg[1]); w.y = pk2(acc[mt][nt][4 * e4 + 2] * r * gg[2], acc[mt][nt][4 * e4 + 3] * r * gg[3]);
;                 *(u32x2*)(op + 32 * mt + 8 * e4) = w;
;             }
;     }
	v_mov_b32_e32 v71, v76
	v_mov_b32_e32 v76, v75
	v_pk_add_f32 v[70:71], v[70:71], v[76:77]
	v_lshl_add_u64 v[72:73], v[72:73], 0, v[150:151]
	v_add_f32_e32 v70, v70, v71
	v_fmamk_f32 v70, v70, 0x3b000000, v1
	v_rsq_f32_e32 v70, v70
	s_nop 0
	v_pk_mul_f32 v[64:65], v[64:65], v[70:71] op_sel_hi:[1,0]
	v_pk_mul_f32 v[62:63], v[62:63], v[70:71] op_sel_hi:[1,0]
	v_pk_mul_f32 v[6:7], v[6:7], v[64:65]
	v_pk_mul_f32 v[8:9], v[8:9], v[62:63]
	v_cvt_pk_bf16_f32 v6, v6, v7
	v_cvt_pk_bf16_f32 v7, v8, v9
	v_and_b32_e32 v222, 32, v0
	v_lshrrev_b32_e32 v222, 2, v222
	v_mov_b32_e32 v223, 0
	v_lshl_add_u64 v[220:221], v[72:73], 0, v[222:223]
	v_mov_b32_e32 v202, v6
	v_mov_b32_e32 v203, v7
	v_pk_mul_f32 v[6:7], v[60:61], v[70:71] op_sel_hi:[1,0]
	s_nop 0
	v_pk_mul_f32 v[2:3], v[2:3], v[6:7]
	v_pk_mul_f32 v[6:7], v[58:59], v[70:71] op_sel_hi:[1,0]
	v_cvt_pk_bf16_f32 v2, v2, v3
	v_pk_mul_f32 v[4:5], v[4:5], v[6:7]
	s_nop 0
	v_cvt_pk_bf16_f32 v3, v4, v5
	v_mov_b32_e32 v204, v2
	v_mov_b32_e32 v205, v3
	s_nop 1
	v_permlane32_swap_b32_e32 v202, v204
	v_permlane32_swap_b32_e32 v203, v205
	global_store_dwordx4 v[220:221], v[202:205], off offset:1024
	v_pk_mul_f32 v[2:3], v[56:57], v[70:71] op_sel_hi:[1,0]
	v_pk_mul_f32 v[4:5], v[54:55], v[70:71] op_sel_hi:[1,0]
	v_pk_mul_f32 v[2:3], v[10:11], v[2:3]
	v_pk_mul_f32 v[4:5], v[12:13], v[4:5]
	v_cvt_pk_bf16_f32 v2, v2, v3
	v_cvt_pk_bf16_f32 v3, v4, v5
	v_mov_b32_e32 v206, v2
	v_mov_b32_e32 v207, v3
	v_pk_mul_f32 v[2:3], v[52:53], v[70:71] op_sel_hi:[1,0]
	v_pk_mul_f32 v[4:5], v[50:51], v[70:71] op_sel_hi:[1,0]
	v_pk_mul_f32 v[2:3], v[114:115], v[2:3]
	v_pk_mul_f32 v[4:5], v[116:117], v[4:5]
	v_cvt_pk_bf16_f32 v2, v2, v3
	v_cvt_pk_bf16_f32 v3, v4, v5
	v_mov_b32_e32 v208, v2
	v_mov_b32_e32 v209, v3
	s_nop 1
	v_permlane32_swap_b32_e32 v206, v208
	v_permlane32_swap_b32_e32 v207, v209
	global_store_dwordx4 v[220:221], v[206:209], off offset:1056
	v_pk_mul_f32 v[2:3], v[36:37], v[70:71] op_sel_hi:[1,0]
	v_pk_mul_f32 v[4:5], v[34:35], v[70:71] op_sel_hi:[1,0]
	v_pk_mul_f32 v[2:3], v[118:119], v[2:3]
	v_pk_mul_f32 v[4:5], v[120:121], v[4:5]
	v_cvt_pk_bf16_f32 v2, v2, v3
	v_cvt_pk_bf16_f32 v3, v4, v5
	v_mov_b32_e32 v210, v2
	v_mov_b32_e32 v211, v3
	v_pk_mul_f32 v[2:3], v[38:39], v[70:71] op_sel_hi:[1,0]
	v_pk_mul_f32 v[4:5], v[40:41], v[70:71] op_sel_hi:[1,0]
	v_pk_mul_f32 v[2:3], v[122:123], v[2:3]
	v_pk_mul_f32 v[4:5], v[124:125], v[4:5]
	v_cvt_pk_bf16_f32 v2, v2, v3
	v_cvt_pk_bf16_f32 v3, v4, v5
	v_mov_b32_e32 v212, v2
	v_mov_b32_e32 v213, v3
	s_nop 1
	v_permlane32_swap_b32_e32 v210, v212
	v_permlane32_swap_b32_e32 v211, v213
	global_store_dwordx4 v[220:221], v[210:213], off offset:1088
	v_pk_mul_f32 v[2:3], v[42:43], v[70:71] op_sel_hi:[1,0]
	v_pk_mul_f32 v[4:5], v[44:45], v[70:71] op_sel_hi:[1,0]
	v_pk_mul_f32 v[2:3], v[98:99], v[2:3]
	v_pk_mul_f32 v[4:5], v[100:101], v[4:5]
	v_cvt_pk_bf16_f32 v2, v2, v3
	v_cvt_pk_bf16_f32 v3, v4, v5
	v_mov_b32_e32 v214, v2
	v_mov_b32_e32 v215, v3
	v_pk_mul_f32 v[2:3], v[46:47], v[70:71] op_sel_hi:[1,0]
	v_pk_mul_f32 v[4:5], v[48:49], v[70:71] op_sel_hi:[1,0]
	v_pk_mul_f32 v[2:3], v[126:127], v[2:3]
	v_pk_mul_f32 v[4:5], v[128:129], v[4:5]
	v_cvt_pk_bf16_f32 v2, v2, v3
	v_cvt_pk_bf16_f32 v3, v4, v5
	v_mov_b32_e32 v216, v2
	v_mov_b32_e32 v217, v3
	s_nop 1
	v_permlane32_swap_b32_e32 v214, v216
	v_permlane32_swap_b32_e32 v215, v217
	global_store_dwordx4 v[220:221], v[214:217], off offset:1120
	v_pk_mul_f32 v[2:3], v[18:19], v[70:71] op_sel_hi:[1,0]
	v_pk_mul_f32 v[4:5], v[20:21], v[70:71] op_sel_hi:[1,0]
	v_pk_mul_f32 v[2:3], v[102:103], v[2:3]
	v_pk_mul_f32 v[4:5], v[104:105], v[4:5]
	v_cvt_pk_bf16_f32 v2, v2, v3
	v_cvt_pk_bf16_f32 v3, v4, v5
	v_mov_b32_e32 v202, v2
	v_mov_b32_e32 v203, v3
	v_pk_mul_f32 v[2:3], v[22:23], v[70:71] op_sel_hi:[1,0]
	v_pk_mul_f32 v[4:5], v[24:25], v[70:71] op_sel_hi:[1,0]
	v_pk_mul_f32 v[2:3], v[106:107], v[2:3]
	v_pk_mul_f32 v[4:5], v[108:109], v[4:5]
	v_cvt_pk_bf16_f32 v2, v2, v3
	v_cvt_pk_bf16_f32 v3, v4, v5
	v_mov_b32_e32 v204, v2
	v_mov_b32_e32 v205, v3
	s_nop 1
	v_permlane32_swap_b32_e32 v202, v204
	v_permlane32_swap_b32_e32 v203, v205
	global_store_dwordx4 v[220:221], v[202:205], off offset:1152
	v_pk_mul_f32 v[2:3], v[26:27], v[70:71] op_sel_hi:[1,0]
	v_pk_mul_f32 v[4:5], v[28:29], v[70:71] op_sel_hi:[1,0]
	v_pk_mul_f32 v[2:3], v[82:83], v[2:3]
	v_pk_mul_f32 v[4:5], v[84:85], v[4:5]
	v_cvt_pk_bf16_f32 v2, v2, v3
	v_cvt_pk_bf16_f32 v3, v4, v5
	v_mov_b32_e32 v206, v2
	v_mov_b32_e32 v207, v3
	v_pk_mul_f32 v[2:3], v[30:31], v[70:71] op_sel_hi:[1,0]
	v_pk_mul_f32 v[4:5], v[32:33], v[70:71] op_sel_hi:[1,0]
	v_pk_mul_f32 v[2:3], v[110:111], v[2:3]
	v_pk_mul_f32 v[4:5], v[112:113], v[4:5]
	v_cvt_pk_bf16_f32 v2, v2, v3
	v_cvt_pk_bf16_f32 v3, v4, v5
	v_mov_b32_e32 v208, v2
	v_mov_b32_e32 v209, v3
	s_nop 1
	v_permlane32_swap_b32_e32 v206, v208
	v_permlane32_swap_b32_e32 v207, v209
	global_store_dwordx4 v[220:221], v[206:209], off offset:1184
	v_pk_mul_f32 v[2:3], v[80:81], v[70:71] op_sel_hi:[1,0]
	v_pk_mul_f32 v[4:5], v[132:133], v[70:71] op_sel_hi:[1,0]
	v_pk_mul_f32 v[2:3], v[86:87], v[2:3]
	v_pk_mul_f32 v[4:5], v[88:89], v[4:5]
	v_cvt_pk_bf16_f32 v2, v2, v3
	v_cvt_pk_bf16_f32 v3, v4, v5
	v_mov_b32_e32 v210, v2
	v_mov_b32_e32 v211, v3
	v_pk_mul_f32 v[2:3], v[134:135], v[70:71] op_sel_hi:[1,0]
	v_pk_mul_f32 v[4:5], v[136:137], v[70:71] op_sel_hi:[1,0]
	v_pk_mul_f32 v[2:3], v[90:91], v[2:3]
	v_pk_mul_f32 v[4:5], v[92:93], v[4:5]
	v_cvt_pk_bf16_f32 v2, v2, v3
	v_cvt_pk_bf16_f32 v3, v4, v5
	v_mov_b32_e32 v212, v2
	v_mov_b32_e32 v213, v3
	s_nop 1
	v_permlane32_swap_b32_e32 v210, v212
	v_permlane32_swap_b32_e32 v211, v213
	global_store_dwordx4 v[220:221], v[210:213], off offset:1216
	v_pk_mul_f32 v[2:3], v[146:147], v[70:71] op_sel_hi:[1,0]
	v_pk_mul_f32 v[4:5], v[148:149], v[70:71] op_sel_hi:[1,0]
	v_pk_mul_f32 v[2:3], v[66:67], v[2:3]
	v_pk_mul_f32 v[4:5], v[68:69], v[4:5]
	v_cvt_pk_bf16_f32 v2, v2, v3
	v_cvt_pk_bf16_f32 v3, v4, v5
	v_mov_b32_e32 v214, v2
	v_mov_b32_e32 v215, v3
	v_pk_mul_f32 v[2:3], v[14:15], v[70:71] op_sel_hi:[1,0]
	v_pk_mul_f32 v[4:5], v[16:17], v[70:71] op_sel_hi:[1,0]
	v_pk_mul_f32 v[2:3], v[94:95], v[2:3]
	v_pk_mul_f32 v[4:5], v[96:97], v[4:5]
	v_cvt_pk_bf16_f32 v2, v2, v3
	v_cvt_pk_bf16_f32 v3, v4, v5
	v_mov_b32_e32 v216, v2
	v_mov_b32_e32 v217, v3
	s_nop 1
	v_permlane32_swap_b32_e32 v214, v216
	v_permlane32_swap_b32_e32 v215, v217
	global_store_dwordx4 v[220:221], v[214:217], off offset:1248
	s_cbranch_scc1 .LBB0_545
